# grid barrier: L1 invalidate (buffer_inv sc1) issued before polling instead of after release; all waves parked so equivalent
# speedup vs baseline: 1.0145x; 1.0145x over previous
.LBB0_20:
	s_or_b64 exec, exec, s[12:13]
	s_waitcnt vmcnt(0)
	s_waitcnt vmcnt(0)

.LBB0_25:
	s_or_b64 exec, exec, s[20:21]
	s_waitcnt vmcnt(0)
	s_waitcnt vmcnt(0)

.LBB0_268:
	s_or_b64 exec, exec, s[0:1]
	v_cvt_f32_u32_e32 v4, v2
	s_waitcnt vmcnt(0)
	v_readfirstlane_b32 s0, v3
	v_sub_u32_e32 v3, 0, v2
	v_rcp_iflag_f32_e32 v4, v4
	v_add_u32_e32 v5, s0, v1
	v_mul_f32_e32 v4, 0x4f7ffffe, v4
	v_cvt_u32_f32_e32 v4, v4
	v_mul_lo_u32 v1, v3, v4
	v_mul_hi_u32 v1, v4, v1
	v_add_u32_e32 v1, v4, v1
	v_mul_hi_u32 v1, v5, v1
	v_mul_lo_u32 v3, v1, v2
	v_sub_u32_e32 v3, v5, v3
	v_add_u32_e32 v4, 1, v1
	v_cmp_ge_u32_e32 vcc, v3, v2
	s_nop 1
	v_cndmask_b32_e32 v1, v1, v4, vcc
	v_sub_u32_e32 v4, v3, v2
	v_cndmask_b32_e32 v3, v3, v4, vcc
	v_add_u32_e32 v4, 1, v1
	v_cmp_ge_u32_e32 vcc, v3, v2
	v_add_u32_e32 v3, 1, v5
	s_nop 0
	v_cndmask_b32_e32 v1, v1, v4, vcc
	v_mul_lo_u32 v4, v2, v1
	v_add_u32_e32 v2, v4, v2
	v_cmp_ne_u32_e32 vcc, v3, v2
	s_and_saveexec_b64 s[0:1], vcc
	s_xor_b64 s[0:1], exec, s[0:1]
	s_cbranch_execz .LBB0_282
	s_waitcnt lgkmcnt(0)
	buffer_inv sc1
	global_load_dword v0, v139, s[90:91] sc1
	s_waitcnt vmcnt(0)
	v_cmp_eq_u32_e32 vcc, v0, v1
	s_and_saveexec_b64 s[20:21], vcc
	s_cbranch_execz .LBB0_281
	s_mov_b32 s42, 1
	s_mov_b64 s[34:35], 0
	s_branch .LBB0_272

.LBB0_285:
	s_or_b64 exec, exec, s[20:21]
	buffer_inv sc1
	s_waitcnt vmcnt(0)
	v_readfirstlane_b32 s0, v2
	v_sub_u32_e32 v3, 0, v0
	s_nop 0
	v_add_u32_e32 v2, s0, v1
	v_cvt_f32_u32_e32 v1, v0
	s_mov_b64 s[0:1], 0
	v_rcp_iflag_f32_e32 v1, v1
	s_nop 0
	v_mul_f32_e32 v1, 0x4f7ffffe, v1
	v_cvt_u32_f32_e32 v1, v1
	v_mul_lo_u32 v3, v3, v1
	v_mul_hi_u32 v3, v1, v3
	v_add_u32_e32 v1, v1, v3
	v_mul_hi_u32 v1, v2, v1
	v_mul_lo_u32 v3, v1, v0
	v_sub_u32_e32 v3, v2, v3
	v_cmp_ge_u32_e32 vcc, v3, v0
	v_add_u32_e32 v4, 1, v1
	v_add_u32_e32 v2, 1, v2
	v_cndmask_b32_e32 v1, v1, v4, vcc
	v_sub_u32_e32 v4, v3, v0
	v_cndmask_b32_e32 v3, v3, v4, vcc
	v_cmp_ge_u32_e32 vcc, v3, v0
	v_add_u32_e32 v3, 1, v1
	s_nop 0
	v_cndmask_b32_e32 v1, v1, v3, vcc
	v_mul_lo_u32 v3, v0, v1
	v_add_u32_e32 v0, v3, v0
	v_cmp_ne_u32_e32 vcc, v2, v0
	s_and_saveexec_b64 s[20:21], vcc
	s_xor_b64 s[20:21], exec, s[20:21]
	s_cbranch_execz .LBB0_297
	s_getpc_b64 s[0:1]
	s_add_u32 s0, s0, g_bar@rel32@lo+13572
	s_addc_u32 s1, s1, g_bar@rel32@hi+13580
	global_load_dword v0, v139, s[0:1] sc1
	s_mov_b64 s[26:27], 0
	s_waitcnt vmcnt(0)
	v_cmp_eq_u32_e32 vcc, v0, v1
	s_and_saveexec_b64 s[0:1], vcc
	s_cbranch_execz .LBB0_296
	s_mov_b32 s42, 1
	s_mov_b64 s[34:35], 0
	s_branch .LBB0_289

.LBB0_937:
	s_or_b64 exec, exec, s[0:1]
	v_cvt_f32_u32_e32 v4, v2
	s_waitcnt vmcnt(0)
	v_readfirstlane_b32 s0, v3
	v_sub_u32_e32 v3, 0, v2
	v_rcp_iflag_f32_e32 v4, v4
	v_add_u32_e32 v5, s0, v1
	v_mul_f32_e32 v4, 0x4f7ffffe, v4
	v_cvt_u32_f32_e32 v4, v4
	v_mul_lo_u32 v1, v3, v4
	v_mul_hi_u32 v1, v4, v1
	v_add_u32_e32 v1, v4, v1
	v_mul_hi_u32 v1, v5, v1
	v_mul_lo_u32 v3, v1, v2
	v_sub_u32_e32 v3, v5, v3
	v_add_u32_e32 v4, 1, v1
	v_cmp_ge_u32_e32 vcc, v3, v2
	s_nop 1
	v_cndmask_b32_e32 v1, v1, v4, vcc
	v_sub_u32_e32 v4, v3, v2
	v_cndmask_b32_e32 v3, v3, v4, vcc
	v_add_u32_e32 v4, 1, v1
	v_cmp_ge_u32_e32 vcc, v3, v2
	v_add_u32_e32 v3, 1, v5
	s_nop 0
	v_cndmask_b32_e32 v1, v1, v4, vcc
	v_mul_lo_u32 v4, v2, v1
	v_add_u32_e32 v2, v4, v2
	v_cmp_ne_u32_e32 vcc, v3, v2
	s_and_saveexec_b64 s[0:1], vcc
	s_xor_b64 s[0:1], exec, s[0:1]
	s_cbranch_execz .LBB0_951
	s_waitcnt lgkmcnt(0)
	buffer_inv sc1
	global_load_dword v0, v139, s[90:91] sc1
	s_waitcnt vmcnt(0)
	v_cmp_eq_u32_e32 vcc, v0, v1
	s_and_saveexec_b64 s[20:21], vcc
	s_cbranch_execz .LBB0_950
	s_mov_b32 s44, 1
	s_mov_b64 s[34:35], 0
	s_branch .LBB0_941

.LBB0_954:
	s_or_b64 exec, exec, s[20:21]
	buffer_inv sc1
	s_waitcnt vmcnt(0)
	v_readfirstlane_b32 s0, v2
	v_sub_u32_e32 v3, 0, v0
	s_nop 0
	v_add_u32_e32 v2, s0, v1
	v_cvt_f32_u32_e32 v1, v0
	s_mov_b64 s[0:1], 0
	v_rcp_iflag_f32_e32 v1, v1
	s_nop 0
	v_mul_f32_e32 v1, 0x4f7ffffe, v1
	v_cvt_u32_f32_e32 v1, v1
	v_mul_lo_u32 v3, v3, v1
	v_mul_hi_u32 v3, v1, v3
	v_add_u32_e32 v1, v1, v3
	v_mul_hi_u32 v1, v2, v1
	v_mul_lo_u32 v3, v1, v0
	v_sub_u32_e32 v3, v2, v3
	v_cmp_ge_u32_e32 vcc, v3, v0
	v_add_u32_e32 v4, 1, v1
	v_add_u32_e32 v2, 1, v2
	v_cndmask_b32_e32 v1, v1, v4, vcc
	v_sub_u32_e32 v4, v3, v0
	v_cndmask_b32_e32 v3, v3, v4, vcc
	v_cmp_ge_u32_e32 vcc, v3, v0
	v_add_u32_e32 v3, 1, v1
	s_nop 0
	v_cndmask_b32_e32 v1, v1, v3, vcc
	v_mul_lo_u32 v3, v0, v1
	v_add_u32_e32 v0, v3, v0
	v_cmp_ne_u32_e32 vcc, v2, v0
	s_and_saveexec_b64 s[20:21], vcc
	s_xor_b64 s[20:21], exec, s[20:21]
	s_cbranch_execz .LBB0_966
	s_getpc_b64 s[0:1]
	s_add_u32 s0, s0, g_bar@rel32@lo+13572
	s_addc_u32 s1, s1, g_bar@rel32@hi+13580
	global_load_dword v0, v139, s[0:1] sc1
	s_mov_b64 s[26:27], 0
	s_waitcnt vmcnt(0)
	v_cmp_eq_u32_e32 vcc, v0, v1
	s_and_saveexec_b64 s[0:1], vcc
	s_cbranch_execz .LBB0_965
	s_mov_b32 s44, 1
	s_mov_b64 s[34:35], 0
	s_branch .LBB0_958

.LBB0_1818:
	s_or_b64 exec, exec, s[0:1]
	v_cvt_f32_u32_e32 v4, v2
	s_waitcnt vmcnt(0)
	v_readfirstlane_b32 s0, v3
	v_sub_u32_e32 v3, 0, v2
	v_rcp_iflag_f32_e32 v4, v4
	v_add_u32_e32 v5, s0, v1
	v_mul_f32_e32 v4, 0x4f7ffffe, v4
	v_cvt_u32_f32_e32 v4, v4
	v_mul_lo_u32 v1, v3, v4
	v_mul_hi_u32 v1, v4, v1
	v_add_u32_e32 v1, v4, v1
	v_mul_hi_u32 v1, v5, v1
	v_mul_lo_u32 v3, v1, v2
	v_sub_u32_e32 v3, v5, v3
	v_add_u32_e32 v4, 1, v1
	v_cmp_ge_u32_e32 vcc, v3, v2
	s_nop 1
	v_cndmask_b32_e32 v1, v1, v4, vcc
	v_sub_u32_e32 v4, v3, v2
	v_cndmask_b32_e32 v3, v3, v4, vcc
	v_add_u32_e32 v4, 1, v1
	v_cmp_ge_u32_e32 vcc, v3, v2
	v_add_u32_e32 v3, 1, v5
	s_nop 0
	v_cndmask_b32_e32 v1, v1, v4, vcc
	v_mul_lo_u32 v4, v2, v1
	v_add_u32_e32 v2, v4, v2
	v_cmp_ne_u32_e32 vcc, v3, v2
	s_and_saveexec_b64 s[0:1], vcc
	s_xor_b64 s[0:1], exec, s[0:1]
	s_cbranch_execz .LBB0_1832
	s_waitcnt lgkmcnt(0)
	buffer_inv sc1
	global_load_dword v0, v139, s[90:91] sc1
	s_waitcnt vmcnt(0)
	v_cmp_eq_u32_e32 vcc, v0, v1
	s_and_saveexec_b64 s[12:13], vcc
	s_cbranch_execz .LBB0_1831
	s_mov_b32 s40, 1
	s_mov_b64 s[18:19], 0
	s_branch .LBB0_1822

.LBB0_1835:
	s_or_b64 exec, exec, s[12:13]
	buffer_inv sc1
	s_waitcnt vmcnt(0)
	v_readfirstlane_b32 s0, v2
	v_sub_u32_e32 v3, 0, v0
	s_nop 0
	v_add_u32_e32 v2, s0, v1
	v_cvt_f32_u32_e32 v1, v0
	s_mov_b64 s[0:1], 0
	v_rcp_iflag_f32_e32 v1, v1
	s_nop 0
	v_mul_f32_e32 v1, 0x4f7ffffe, v1
	v_cvt_u32_f32_e32 v1, v1
	v_mul_lo_u32 v3, v3, v1
	v_mul_hi_u32 v3, v1, v3
	v_add_u32_e32 v1, v1, v3
	v_mul_hi_u32 v1, v2, v1
	v_mul_lo_u32 v3, v1, v0
	v_sub_u32_e32 v3, v2, v3
	v_cmp_ge_u32_e32 vcc, v3, v0
	v_add_u32_e32 v4, 1, v1
	v_add_u32_e32 v2, 1, v2
	v_cndmask_b32_e32 v1, v1, v4, vcc
	v_sub_u32_e32 v4, v3, v0
	v_cndmask_b32_e32 v3, v3, v4, vcc
	v_cmp_ge_u32_e32 vcc, v3, v0
	v_add_u32_e32 v3, 1, v1
	s_nop 0
	v_cndmask_b32_e32 v1, v1, v3, vcc
	v_mul_lo_u32 v3, v0, v1
	v_add_u32_e32 v0, v3, v0
	v_cmp_ne_u32_e32 vcc, v2, v0
	s_and_saveexec_b64 s[12:13], vcc
	s_xor_b64 s[12:13], exec, s[12:13]
	s_cbranch_execz .LBB0_1847
	s_getpc_b64 s[0:1]
	s_add_u32 s0, s0, g_bar@rel32@lo+13572
	s_addc_u32 s1, s1, g_bar@rel32@hi+13580
	global_load_dword v0, v139, s[0:1] sc1
	s_mov_b64 s[18:19], 0
	s_waitcnt vmcnt(0)
	v_cmp_eq_u32_e32 vcc, v0, v1
	s_and_saveexec_b64 s[0:1], vcc
	s_cbranch_execz .LBB0_1846
	s_mov_b32 s40, 1
	s_branch .LBB0_1839
